# attention loops: tile staging (ds_write of tile t+1 and loads of t+2) moved from loop top to after QK/bias, on top of MoBA bias rewrite
# speedup vs baseline: 1.0238x; 1.0042x over previous
; template <int DQK, bool MOBA>
; __device__ __forceinline__ void attn_unit(const Args& A, int b, int h, int qb, lptr lds) {
;     ...
;     f32x16 o[4];
; #pragma unroll
;     for (int d = 0; d < 4; ++d)
; #pragma unroll
;         for (int r = 0; r < 16; ++r) o[d][r] = 0.f;
;     float lrow = 0.f;
;     ATT_LOAD(0); ATT_WRITE(0);
;     if (NT > 1) ATT_LOAD(1);
;     __syncthreads();
;     for (int t = 0; t < NT; ++t) {
;         const int buf = t & 1;
;         if (t + 1 < NT) { ATT_WRITE(buf ^ 1); if (t + 2 < NT) ATT_LOAD(t + 2); }
.LBB0_780:
	s_add_i32 s0, s15, -1
	s_cmp_ge_u32 s0, s19
	s_cbranch_scc1 .Lmoba_hd_done_a
	s_xor_b32 s4, s24, 1
	s_mul_i32 s0, s4, 0x4400
	s_mul_i32 s1, s4, 0x5000
	v_add3_u32 v232, s0, v167, v166
	s_waitcnt vmcnt(0)
	ds_write_b128 v232, v[144:147]
	v_add3_u32 v232, s0, v163, v166
	ds_write_b128 v232, v[148:151]
	v_add3_u32 v232, s1, v174, v166
	ds_write_b128 v232, v[152:155] offset:34816
	v_add3_u32 v232, s1, v175, v166
	ds_write_b128 v232, v[156:159] offset:34816
	s_and_saveexec_b64 s[0:1], s[40:41]
	v_lshl_add_u32 v232, s4, 8, v178
	v_lshlrev_b32_e32 v173, 2, v173
	ds_write_b32 v232, v173
	s_or_b64 exec, exec, s[0:1]
	s_cmp_ge_u32 s15, s19
	s_cbranch_scc1 .Lmoba_hd_done_a
	s_add_i32 s0, s18, s15
	s_add_i32 s1, s15, -4
	s_add_i32 s6, s15, -2
	s_cmp_lt_u32 s6, 2
	s_cselect_b32 s0, s0, s1
	s_lshl_b32 s4, s0, 6
	s_add_i32 s4, s4, s70
	s_mul_i32 s7, s4, 0x1800
	s_mul_hi_i32 s5, s4, 0x1800
	s_add_u32 s0, s20, s7
	s_addc_u32 s1, s21, s5
	v_lshl_add_u64 v[232:233], s[0:1], 0, v[164:165]
	v_lshl_add_u64 v[234:235], s[0:1], 0, v[168:169]
	s_add_u32 s0, s22, s7
	v_lshl_add_u64 v[232:233], v[232:233], 0, v[180:181]
	s_addc_u32 s1, s23, s5
	v_lshl_add_u64 v[234:235], v[234:235], 0, v[180:181]
	global_load_dwordx4 v[144:147], v[232:233], off
	global_load_dwordx4 v[148:151], v[234:235], off
	v_lshl_add_u64 v[232:233], s[0:1], 0, v[164:165]
	v_lshl_add_u64 v[232:233], v[232:233], 0, v[180:181]
	v_lshl_add_u64 v[234:235], s[0:1], 0, v[168:169]
	v_lshl_add_u64 v[234:235], v[234:235], 0, v[180:181]
	global_load_dwordx4 v[152:155], v[232:233], off
	global_load_dwordx4 v[156:159], v[234:235], off
	s_and_saveexec_b64 s[0:1], s[40:41]
	s_cbranch_execz .Lmoba_hd_pos_a
	v_add_u32_e32 v232, s4, v162
	v_ashrrev_i32_e32 v233, 31, v232
	v_lshl_add_u64 v[232:233], v[232:233], 2, s[54:55]
	global_load_dword v173, v[232:233], off

; template <int DQK, bool MOBA>
; __device__ __forceinline__ void attn_unit(const Args& A, int b, int h, int qb, lptr lds) {
;     ...
;     for (int t = 0; t < NT; ++t) {
;         const int buf = t & 1;
;         if (t + 1 < NT) { ATT_WRITE(buf ^ 1); if (t + 2 < NT) ATT_LOAD(t + 2); }
;         const int tt = t & 3; const bool diag = t < 4; const int blk = diag ? own : ((t - 4) >> 2);
;         const bool lsel = diag || ((sel >> blk) & 1u);
;         bool act;
;         if (diag) act = (64 * tt < 32 * (wid + 1));
;         else act = MOBA ? (__ballot(lsel) != 0ull) : true;
.LBB0_782:
	s_add_i32 s6, s15, -2
	s_and_b32 s24, s6, 1
.LBB0_789:
	s_cmp_lt_u32 s6, 4
	s_cselect_b64 s[4:5], -1, 0
	s_add_i32 s0, s15, -6
	s_ashr_i32 s0, s0, 2
	v_lshrrev_b32_e32 v80, s0, v172
	v_and_b32_e32 v80, 1, v80
	s_cmp_gt_u32 s6, 3
	v_cmp_eq_u32_e64 s[0:1], 1, v80
	s_mov_b64 s[28:29], -1
	s_cbranch_scc0 .LBB0_792
	v_cndmask_b32_e64 v80, 0, 1, s[0:1]
	v_cmp_ne_u32_e32 vcc, 0, v80
	s_cmp_lg_u64 vcc, 0
	s_cselect_b64 s[6:7], -1, 0
	s_cbranch_execz .LBB0_793

; template <int DQK, bool MOBA>
; __device__ __forceinline__ void attn_unit(const Args& A, int b, int h, int qb, lptr lds) {
;     ...
;     f32x16 o[4];
; #pragma unroll
;     for (int d = 0; d < 4; ++d)
; #pragma unroll
;         for (int r = 0; r < 16; ++r) o[d][r] = 0.f;
;     float lrow = 0.f;
;     ATT_LOAD(0); ATT_WRITE(0);
;     if (NT > 1) ATT_LOAD(1);
;     __syncthreads();
;     for (int t = 0; t < NT; ++t) {
;         const int buf = t & 1;
;         if (t + 1 < NT) { ATT_WRITE(buf ^ 1); if (t + 2 < NT) ATT_LOAD(t + 2); }
.LBB0_810:
	s_xor_b32 s0, s44, 1
	s_mul_i32 s1, s0, 0x6400
	s_mul_i32 s0, s0, 0x5000
	v_add3_u32 v246, s1, v200, v186
	s_waitcnt vmcnt(0)
	ds_write_b128 v246, v[176:179]
	v_add3_u32 v246, s1, v201, v186
	ds_write_b128 v246, v[168:171]
	v_add3_u32 v246, s1, v210, v188
	ds_write_b128 v246, v[172:175] offset:256
	v_add3_u32 v246, s0, v211, v186
	ds_write_b128 v246, v[164:167] offset:51200
	v_add3_u32 v246, s0, v212, v186
	ds_write_b128 v246, v[160:163] offset:51200
	s_cmp_ge_u32 s5, s26
	s_cbranch_scc1 .Lmla_hd_done_a
	s_add_i32 s0, s25, s5
	s_add_i32 s1, s5, -4
	s_cmp_lt_u32 s45, 2
	s_cselect_b32 s0, s0, s1
	s_lshl_b32 s0, s0, 6
	s_add_i32 s0, s0, s24
	s_ashr_i32 s1, s0, 31
	s_lshl_b64 s[46:47], s[0:1], 11
	s_add_u32 s48, s4, s46
	s_addc_u32 s49, s15, s47
	v_lshl_add_u64 v[248:249], s[48:49], 0, v[192:193]
	v_lshl_add_u64 v[248:249], v[248:249], 0, v[180:181]
	v_lshl_add_u64 v[250:251], s[48:49], 0, v[194:195]
	v_lshl_add_u64 v[250:251], v[250:251], 0, v[180:181]
	global_load_dwordx4 v[176:179], v[248:249], off
	global_load_dwordx4 v[168:171], v[250:251], off
	v_add_u32_e32 v248, s0, v199
	v_ashrrev_i32_e32 v249, 31, v248
	s_add_u32 s0, s6, s46
	v_lshlrev_b64 v[248:249], 7, v[248:249]
	s_addc_u32 s1, s7, s47
	v_lshl_add_u64 v[248:249], v[190:191], 0, v[248:249]
	v_lshl_add_u64 v[250:251], s[0:1], 0, v[192:193]
	v_lshl_add_u64 v[250:251], v[250:251], 0, v[180:181]
	global_load_dwordx4 v[172:175], v[248:249], off
	global_load_dwordx4 v[164:167], v[250:251], off
	v_lshl_add_u64 v[248:249], s[0:1], 0, v[194:195]
	v_lshl_add_u64 v[248:249], v[248:249], 0, v[180:181]
	global_load_dwordx4 v[160:163], v[248:249], off

; #define LAS __attribute__((address_space(3)))
; #define MFMA32(a, b, c) __builtin_amdgcn_mfma_f32_32x32x16_bf16((a), (b), (c), 0, 0, 0)
; template <int DQK, bool MOBA>
; __device__ __forceinline__ void attn_unit(const Args& A, int b, int h, int qb, lptr lds) {
;     ...
;     for (int t = 0; t < NT; ++t) {
;         const int buf = t & 1;
;         if (t + 1 < NT) { ATT_WRITE(buf ^ 1); if (t + 2 < NT) ATT_LOAD(t + 2); }
;         const int tt = t & 3; const bool diag = t < 4; const int blk = diag ? own : ((t - 4) >> 2);
;         const bool lsel = diag || ((sel >> blk) & 1u);
;         bool act;
;         if (diag) act = (64 * tt < 32 * (wid + 1));
;         else act = MOBA ? (__ballot(lsel) != 0ull) : true;
;         if (act) {
;             lptr kb = lds + L::OFF_K + buf * L::KBUF + r32 * L::KROW + 16 * hi;
;             f32x16 s0, s1;
; #pragma unroll
;             for (int r = 0; r < 16; ++r) { s0[r] = negm; s1[r] = negm; }
;             {
;                 bf16x8 ka[2][2], kc[2][2];
; #pragma unroll
;                 for (int i = 0; i < 2; ++i) { ka[0][i] = *(const LAS bf16x8*)(kb + 32 * i); kc[0][i] = *(const LAS bf16x8*)(kb + 32 * L::KROW + 32 * i); }
;                 __builtin_amdgcn_sched_barrier(0);
; #pragma unroll
;                 for (int sb = 0; sb < NS; sb += 2) {
;                     const int cur = (sb >> 1) & 1, nxt = cur ^ 1;
;                     if (sb + 2 < NS) {
; #pragma unroll
;                         for (int i = 0; i < 2; ++i) { ka[nxt][i] = *(const LAS bf16x8*)(kb + 32 * (sb + 2 + i)); kc[nxt][i] = *(const LAS bf16x8*)(kb + 32 * L::KROW + 32 * (sb + 2 + i)); }
;                     }
;                     __builtin_amdgcn_sched_barrier(0);
; #pragma unroll
;                     for (int i = 0; i < 2; ++i) { s0 = MFMA32(ka[cur][i], qf[sb + i], s0); s1 = MFMA32(kc[cur][i], qf[sb + i], s1); }
;                     __builtin_amdgcn_sched_barrier(0);
;                 }
;             }
.LBB0_812:
	s_add_i32 s45, s5, -2
	s_and_b32 s44, s45, 1
.LBB0_814:
	s_cmp_lt_u32 s45, 4
	s_cselect_b64 s[0:1], -1, 0
	s_cmp_gt_u32 s45, 3
	s_cselect_b64 s[46:47], -1, 0
	s_cmp_le_i32 s27, s23
	s_cselect_b64 s[48:49], -1, 0
	s_or_b64 s[46:47], s[46:47], s[48:49]
	s_andn2_b64 vcc, exec, s[46:47]
	s_cbranch_vccnz .Lmla_skip
	s_mul_i32 s34, s44, 0x6400
	v_add_u32_e32 v189, s34, v213
	ds_read_b128 v[80:83], v189
	ds_read_b128 v[214:217], v189 offset:32
	ds_read_b128 v[218:221], v189 offset:12800
	ds_read_b128 v[222:225], v189 offset:12832
	ds_read_b128 v[226:229], v189 offset:64
	ds_read_b128 v[230:233], v189 offset:96
	ds_read_b128 v[234:237], v189 offset:12864
	ds_read_b128 v[238:241], v189 offset:12896
	s_waitcnt lgkmcnt(7)
	v_mfma_f32_32x32x16_bf16 v[96:111], v[80:83], v[112:115], v[64:79]
	s_waitcnt lgkmcnt(5)
	v_mfma_f32_32x32x16_bf16 v[80:95], v[218:221], v[112:115], v[64:79]
	v_mfma_f32_32x32x16_bf16 v[96:111], v[214:217], v[116:119], v[96:111]
	s_waitcnt lgkmcnt(4)
	v_mfma_f32_32x32x16_bf16 v[80:95], v[222:225], v[116:119], v[80:95]
	ds_read_b128 v[214:217], v189 offset:128
	ds_read_b128 v[218:221], v189 offset:160
	ds_read_b128 v[222:225], v189 offset:12928
	ds_read_b128 v[242:245], v189 offset:12960
	s_waitcnt lgkmcnt(7)
	v_mfma_f32_32x32x16_bf16 v[96:111], v[226:229], v[120:123], v[96:111]
	s_waitcnt lgkmcnt(5)
	v_mfma_f32_32x32x16_bf16 v[80:95], v[234:237], v[120:123], v[80:95]
	v_mfma_f32_32x32x16_bf16 v[96:111], v[230:233], v[124:127], v[96:111]
	s_waitcnt lgkmcnt(4)
	v_mfma_f32_32x32x16_bf16 v[80:95], v[238:241], v[124:127], v[80:95]
	ds_read_b128 v[226:229], v189 offset:192
	ds_read_b128 v[230:233], v189 offset:224
	ds_read_b128 v[234:237], v189 offset:12992
	ds_read_b128 v[238:241], v189 offset:13024
	s_waitcnt lgkmcnt(7)
	v_mfma_f32_32x32x16_bf16 v[96:111], v[214:217], v[128:131], v[96:111]
	s_waitcnt lgkmcnt(5)
	v_mfma_f32_32x32x16_bf16 v[80:95], v[222:225], v[128:131], v[80:95]
	v_mfma_f32_32x32x16_bf16 v[96:111], v[218:221], v[132:135], v[96:111]
	s_waitcnt lgkmcnt(4)
	v_mfma_f32_32x32x16_bf16 v[80:95], v[242:245], v[132:135], v[80:95]
	ds_read_b128 v[214:217], v189 offset:256
	ds_read_b128 v[218:221], v189 offset:288
	ds_read_b128 v[222:225], v189 offset:13056
	ds_read_b128 v[242:245], v189 offset:13088
	s_waitcnt lgkmcnt(7)
	v_mfma_f32_32x32x16_bf16 v[96:111], v[226:229], v[136:139], v[96:111]
	s_waitcnt lgkmcnt(5)
	v_mfma_f32_32x32x16_bf16 v[80:95], v[234:237], v[136:139], v[80:95]
	v_mfma_f32_32x32x16_bf16 v[96:111], v[230:233], v[140:143], v[96:111]
	s_waitcnt lgkmcnt(4)
	v_mfma_f32_32x32x16_bf16 v[80:95], v[238:241], v[140:143], v[80:95]
	ds_read_b128 v[226:229], v189 offset:320
	ds_read_b128 v[230:233], v189 offset:352
	ds_read_b128 v[234:237], v189 offset:13120
	ds_read_b128 v[238:241], v189 offset:13152
	s_waitcnt lgkmcnt(7)
	v_mfma_f32_32x32x16_bf16 v[96:111], v[214:217], v[148:151], v[96:111]
	s_waitcnt lgkmcnt(5)
	v_mfma_f32_32x32x16_bf16 v[80:95], v[222:225], v[148:151], v[80:95]
	v_mfma_f32_32x32x16_bf16 v[96:111], v[218:221], v[156:159], v[96:111]
	s_waitcnt lgkmcnt(4)
	v_mfma_f32_32x32x16_bf16 v[80:95], v[242:245], v[156:159], v[80:95]
	s_waitcnt lgkmcnt(3)
	v_mfma_f32_32x32x16_bf16 v[96:111], v[226:229], v[144:147], v[96:111]
	s_waitcnt lgkmcnt(1)
	v_mfma_f32_32x32x16_bf16 v[80:95], v[234:237], v[144:147], v[80:95]
	v_mfma_f32_32x32x16_bf16 v[96:111], v[230:233], v[152:155], v[96:111]
	s_waitcnt lgkmcnt(0)
	v_mfma_f32_32x32x16_bf16 v[80:95], v[238:241], v[152:155], v[80:95]
	s_andn2_b64 vcc, exec, s[0:1]
	s_cbranch_vccnz .LBB0_810
; template <int DQK, bool MOBA>
; __device__ __forceinline__ void attn_unit(const Args& A, int b, int h, int qb, lptr lds) {
;     ...
;             if (diag) {
; #pragma unroll
;                 for (int r = 0; r < 16; ++r) {
;                     const int kl = 64 * tt + (r & 3) + 8 * (r >> 2) + 4 * hi;
;                     if (kl > qrel) s0[r] = NEG;
;                     if (kl + 32 > qrel) s1[r] = NEG;
;                 }
;             }
	v_add_u32_e32 v189, s27, v183
	v_add_u32_e32 v203, 32, v189
	v_cmp_le_i32_e32 vcc, v203, v197
	v_add_u32_e32 v203, 33, v189
	s_nop 5
	v_cndmask_b32_e32 v80, v209, v80, vcc
	v_cmp_lt_i32_e32 vcc, v189, v197
	s_nop 1
	v_cndmask_b32_e32 v97, v209, v97, vcc
	v_cmp_le_i32_e32 vcc, v189, v197
	s_nop 1
	v_cndmask_b32_e32 v96, v209, v96, vcc
	v_cmp_le_i32_e32 vcc, v203, v197
	v_add_u32_e32 v203, 2, v189
	s_nop 0
	v_cndmask_b32_e32 v81, v209, v81, vcc
	v_cmp_le_i32_e32 vcc, v203, v197
	v_add_u32_e32 v203, 34, v189
	s_nop 0
	v_cndmask_b32_e32 v98, v209, v98, vcc
	v_cmp_le_i32_e32 vcc, v203, v197
	v_add_u32_e32 v203, 3, v189
	s_nop 0
	v_cndmask_b32_e32 v82, v209, v82, vcc
	v_cmp_le_i32_e32 vcc, v203, v197
	v_add_u32_e32 v203, 35, v189
	s_nop 0
	v_cndmask_b32_e32 v99, v209, v99, vcc
	v_cmp_le_i32_e32 vcc, v203, v197
	v_add_u32_e32 v203, 8, v189
	s_nop 0
	v_cndmask_b32_e32 v83, v209, v83, vcc
	v_cmp_le_i32_e32 vcc, v203, v197
	v_add_u32_e32 v203, 40, v189
	s_nop 0
	v_cndmask_b32_e32 v100, v209, v100, vcc
	v_cmp_le_i32_e32 vcc, v203, v197
	v_add_u32_e32 v203, 9, v189
	s_nop 0
	v_cndmask_b32_e32 v84, v209, v84, vcc
	v_cmp_le_i32_e32 vcc, v203, v197
	v_add_u32_e32 v203, 41, v189
	s_nop 0
	v_cndmask_b32_e32 v101, v209, v101, vcc
	v_cmp_le_i32_e32 vcc, v203, v197
	v_add_u32_e32 v203, 10, v189
	s_nop 0
	v_cndmask_b32_e32 v85, v209, v85, vcc
	v_cmp_le_i32_e32 vcc, v203, v197
	v_add_u32_e32 v203, 42, v189
	s_nop 0
	v_cndmask_b32_e32 v102, v209, v102, vcc
	v_cmp_le_i32_e32 vcc, v203, v197
	v_add_u32_e32 v203, 11, v189
	s_nop 0
	v_cndmask_b32_e32 v86, v209, v86, vcc
	v_cmp_le_i32_e32 vcc, v203, v197
	v_add_u32_e32 v203, 43, v189
	s_nop 0
	v_cndmask_b32_e32 v103, v209, v103, vcc
	v_cmp_le_i32_e32 vcc, v203, v197
	v_add_u32_e32 v203, 16, v189
	s_nop 0
	v_cndmask_b32_e32 v87, v209, v87, vcc
	v_cmp_le_i32_e32 vcc, v203, v197
	v_add_u32_e32 v203, 48, v189
	s_nop 0
	v_cndmask_b32_e32 v104, v209, v104, vcc
	v_cmp_le_i32_e32 vcc, v203, v197
	v_add_u32_e32 v203, 17, v189
	s_nop 0
	v_cndmask_b32_e32 v88, v209, v88, vcc
	v_cmp_le_i32_e32 vcc, v203, v197
	v_add_u32_e32 v203, 49, v189
	s_nop 0
	v_cndmask_b32_e32 v105, v209, v105, vcc
	v_cmp_le_i32_e32 vcc, v203, v197
	v_add_u32_e32 v203, 18, v189
	s_nop 0
	v_cndmask_b32_e32 v89, v209, v89, vcc
	v_cmp_le_i32_e32 vcc, v203, v197
	v_add_u32_e32 v203, 50, v189
	s_nop 0
	v_cndmask_b32_e32 v106, v209, v106, vcc
	v_cmp_le_i32_e32 vcc, v203, v197
	v_add_u32_e32 v203, 19, v189
	s_nop 0
	v_cndmask_b32_e32 v90, v209, v90, vcc
	v_cmp_le_i32_e32 vcc, v203, v197
	v_add_u32_e32 v203, 51, v189
	s_nop 0
	v_cndmask_b32_e32 v107, v209, v107, vcc
	v_cmp_le_i32_e32 vcc, v203, v197
	v_add_u32_e32 v203, 24, v189
	s_nop 0
	v_cndmask_b32_e32 v91, v209, v91, vcc
	v_cmp_le_i32_e32 vcc, v203, v197
	v_add_u32_e32 v203, 56, v189
	s_nop 0
	v_cndmask_b32_e32 v108, v209, v108, vcc
	v_cmp_le_i32_e32 vcc, v203, v197
	v_add_u32_e32 v203, 25, v189
	s_nop 0
	v_cndmask_b32_e32 v92, v209, v92, vcc
	v_cmp_le_i32_e32 vcc, v203, v197
	v_add_u32_e32 v203, 57, v189
	s_nop 0
	v_cndmask_b32_e32 v109, v209, v109, vcc
	v_cmp_le_i32_e32 vcc, v203, v197
	v_add_u32_e32 v203, 26, v189
	s_nop 0
	v_cndmask_b32_e32 v93, v209, v93, vcc
	v_cmp_le_i32_e32 vcc, v203, v197
	v_add_u32_e32 v203, 58, v189
	s_nop 0
	v_cndmask_b32_e32 v110, v209, v110, vcc
	v_cmp_le_i32_e32 vcc, v203, v197
	v_add_u32_e32 v203, 27, v189
	v_add_u32_e32 v189, 59, v189
	v_cndmask_b32_e32 v94, v209, v94, vcc
	v_cmp_le_i32_e32 vcc, v203, v197
	s_nop 1
	v_cndmask_b32_e32 v111, v209, v111, vcc
	v_cmp_le_i32_e32 vcc, v189, v197
	s_nop 1
	v_cndmask_b32_e32 v95, v209, v95, vcc
	s_branch .LBB0_810
